# combined small edits on the XCD-local version: P4b loads two k-tiles ahead with interleaved LDS stores, permlane row reductions in the P4b/P6 epilogues, 4-deep expert-table conversion loop, P3 step LD
# speedup vs baseline: 1.0036x; 1.0036x over previous
; __device__ __forceinline__ u16 f2bf(float f) { return (u16)(pack2(f, f) & 0xffffu); }
; __device__ __forceinline__ float bf2f(u16 h) { return __uint_as_float(((unsigned)h) << 16); }
; __device__ __forceinline__ float sum32(float v) { v = dpp_row_sum16(v); v += __shfl_xor(v, 16); return v; }
; __device__ __forceinline__ int rowmap(int e, int lane) { return (e & 3) + 8 * (e >> 2) + 4 * (lane >> 5); }
; __device__ __forceinline__ void seq_item(const Params& p, int item, char* smem, const bool write_o = true) {
;     ...
;   for (int n = 0; n < 32; n++) {
; #pragma unroll
;     for (int e = 0; e < 16; e++) STs[rowmap(e, lane) * 136 + dcol] = f2bf(S[e]);
;     *(uint4*)&VTs[(tid >> 3) * 72 + (tid & 7) * 8] = vt4;
;     __syncthreads();
;     const int tok0 = b * 2048 + n * 64;
;     if (w < 2) {
;       f32x16 o;
; #pragma unroll
;       for (int e = 0; e < 16; e++) o[e] = bf2f(o0[e]);
; #pragma unroll
;       for (int ks = 0; ks < 8; ks++) {
;         bf16x8 bb = *(const bf16x8*)&STs[r * 136 + ks * 16 + hh];
;         o = mfma16(qbf[ks], bb, o);
;       }
; #pragma unroll
;       for (int e = 0; e < 16; e++) {
;         const int t = w * 32 + rowmap(e, lane);
;         if (write_o) Om[(size_t)(tok0 + t) * 512 + h * 128 + sl * 32 + r] = f2bf(o[e]);
;         float sq = sum32(o[e] * o[e]);
;         if (r == 0) SSQO[((size_t)(tok0 + t) * 4 + h) * 4 + sl] = sq;
;       }
.Lp3_pf_done:
	ds_read_b128 v[192:195], v83
	ds_read_b128 v[196:199], v83 offset:32
	ds_read_b128 v[200:203], v83 offset:64
	ds_read_b128 v[204:207], v83 offset:96
	ds_read_b128 v[208:211], v83 offset:128
	ds_read_b128 v[212:215], v83 offset:160
	ds_read_b128 v[216:219], v83 offset:192
	ds_read_b128 v[220:223], v83 offset:224
	ds_read_b128 v[188:191], v80 offset:8704
	ds_read_b128 v[224:227], v80 offset:8736
	ds_read_b128 v[228:231], v80 offset:8768
	ds_read_b128 v[242:245], v80 offset:8800
	s_and_saveexec_b64 s[0:1], s[4:5]
	s_cbranch_execz .LBB0_1055
	v_lshlrev_b32_e32 v0, 16, v57
	v_lshlrev_b32_e32 v26, 16, v61
	v_lshlrev_b32_e32 v27, 16, v87
	v_lshlrev_b32_e32 v28, 16, v88
	v_lshlrev_b32_e32 v29, 16, v89
	v_lshlrev_b32_e32 v30, 16, v90
	v_lshlrev_b32_e32 v31, 16, v91
	v_lshlrev_b32_e32 v32, 16, v92
	v_lshlrev_b32_e32 v33, 16, v93
	v_lshlrev_b32_e32 v63, 16, v94
	v_lshlrev_b32_e32 v65, 16, v95
	v_lshlrev_b32_e32 v78, 16, v96
	v_lshlrev_b32_e32 v79, 16, v97
	v_lshlrev_b32_e32 v101, 16, v98
	v_lshlrev_b32_e32 v186, 16, v99
	v_lshlrev_b32_e32 v187, 16, v100
	v_accvgpr_write_b32 a0, v0
	v_accvgpr_write_b32 a1, v26
	v_accvgpr_write_b32 a2, v27
	v_accvgpr_write_b32 a3, v28
	v_accvgpr_write_b32 a4, v29
	v_accvgpr_write_b32 a5, v30
	v_accvgpr_write_b32 a6, v31
	v_accvgpr_write_b32 a7, v32
	v_accvgpr_write_b32 a8, v33
	v_accvgpr_write_b32 a9, v63
	v_accvgpr_write_b32 a10, v65
	v_accvgpr_write_b32 a11, v78
	v_accvgpr_write_b32 a12, v79
	v_accvgpr_write_b32 a13, v101
	v_accvgpr_write_b32 a14, v186
	v_accvgpr_write_b32 a15, v187
	v_cmp_lt_i32_e32 vcc, v85, v86
	v_lshl_add_u64 v[78:79], v[72:73], 0, s[22:23]
	s_waitcnt lgkmcnt(11)
	v_mfma_f32_32x32x16_bf16 a[0:15], v[154:157], v[192:195], a[0:15]
	v_cndmask_b32_e32 v0, v84, v85, vcc
	v_lshlrev_b32_e32 v63, 2, v0
	s_waitcnt lgkmcnt(10)
	v_mfma_f32_32x32x16_bf16 a[0:15], v[158:161], v[196:199], a[0:15]
	s_waitcnt lgkmcnt(9)
	v_mfma_f32_32x32x16_bf16 a[0:15], v[162:165], v[200:203], a[0:15]
	s_waitcnt lgkmcnt(8)
	v_mfma_f32_32x32x16_bf16 a[0:15], v[166:169], v[204:207], a[0:15]
	s_waitcnt lgkmcnt(7)
	v_mfma_f32_32x32x16_bf16 a[0:15], v[170:173], v[208:211], a[0:15]
	s_waitcnt lgkmcnt(6)
	v_mfma_f32_32x32x16_bf16 a[0:15], v[174:177], v[212:215], a[0:15]
	s_waitcnt lgkmcnt(5)
	v_mfma_f32_32x32x16_bf16 a[0:15], v[178:181], v[216:219], a[0:15]
	v_add_co_u32_e32 v20, vcc, s35, v78
	s_nop 1
	v_addc_co_u32_e32 v21, vcc, 0, v79, vcc
	s_waitcnt lgkmcnt(4)
	v_mfma_f32_32x32x16_bf16 a[0:15], v[182:185], v[220:223], a[0:15]
	s_nop 11
	v_accvgpr_read_b32 v18, a0
	v_accvgpr_read_b32 v19, a1
	v_accvgpr_read_b32 v20, a2
	v_accvgpr_read_b32 v21, a3
	v_accvgpr_read_b32 v22, a4
	v_accvgpr_read_b32 v23, a5
	v_accvgpr_read_b32 v24, a6
	v_accvgpr_read_b32 v25, a7
	v_accvgpr_read_b32 v26, a8
	v_accvgpr_read_b32 v27, a9
	v_accvgpr_read_b32 v28, a10
	v_accvgpr_read_b32 v29, a11
	v_accvgpr_read_b32 v30, a12
	v_accvgpr_read_b32 v31, a13
	v_accvgpr_read_b32 v32, a14
	v_accvgpr_read_b32 v33, a15
	v_mul_f32_e32 v57, v18, v18
	v_mul_f32_e32 v61, v19, v19
	v_mul_f32_e32 v87, v20, v20
	v_mul_f32_e32 v88, v21, v21
	v_mul_f32_e32 v89, v22, v22
	v_mul_f32_e32 v90, v23, v23
	v_mul_f32_e32 v91, v24, v24
	v_mul_f32_e32 v92, v25, v25
	v_mul_f32_e32 v93, v26, v26
	v_mul_f32_e32 v94, v27, v27
	v_mul_f32_e32 v95, v28, v28
	v_mul_f32_e32 v96, v29, v29
	v_mul_f32_e32 v97, v30, v30
	v_mul_f32_e32 v98, v31, v31
	v_mul_f32_e32 v99, v32, v32
	v_mul_f32_e32 v100, v33, v33
	v_mov_b32_dpp v57, v57 quad_perm:[1,0,3,2] row_mask:0xf bank_mask:0xf bound_ctrl:1
	v_mov_b32_dpp v61, v61 quad_perm:[1,0,3,2] row_mask:0xf bank_mask:0xf bound_ctrl:1
	v_mov_b32_dpp v87, v87 quad_perm:[1,0,3,2] row_mask:0xf bank_mask:0xf bound_ctrl:1
	v_mov_b32_dpp v88, v88 quad_perm:[1,0,3,2] row_mask:0xf bank_mask:0xf bound_ctrl:1
	v_mov_b32_dpp v89, v89 quad_perm:[1,0,3,2] row_mask:0xf bank_mask:0xf bound_ctrl:1
	v_mov_b32_dpp v90, v90 quad_perm:[1,0,3,2] row_mask:0xf bank_mask:0xf bound_ctrl:1
	v_mov_b32_dpp v91, v91 quad_perm:[1,0,3,2] row_mask:0xf bank_mask:0xf bound_ctrl:1
	v_mov_b32_dpp v92, v92 quad_perm:[1,0,3,2] row_mask:0xf bank_mask:0xf bound_ctrl:1
	v_mov_b32_dpp v93, v93 quad_perm:[1,0,3,2] row_mask:0xf bank_mask:0xf bound_ctrl:1
	v_mov_b32_dpp v94, v94 quad_perm:[1,0,3,2] row_mask:0xf bank_mask:0xf bound_ctrl:1
	v_mov_b32_dpp v95, v95 quad_perm:[1,0,3,2] row_mask:0xf bank_mask:0xf bound_ctrl:1
	v_mov_b32_dpp v96, v96 quad_perm:[1,0,3,2] row_mask:0xf bank_mask:0xf bound_ctrl:1
	v_mov_b32_dpp v97, v97 quad_perm:[1,0,3,2] row_mask:0xf bank_mask:0xf bound_ctrl:1
	v_mov_b32_dpp v98, v98 quad_perm:[1,0,3,2] row_mask:0xf bank_mask:0xf bound_ctrl:1
	v_mov_b32_dpp v99, v99 quad_perm:[1,0,3,2] row_mask:0xf bank_mask:0xf bound_ctrl:1
	v_mov_b32_dpp v100, v100 quad_perm:[1,0,3,2] row_mask:0xf bank_mask:0xf bound_ctrl:1
	v_fmac_f32_e32 v57, v18, v18
	v_fmac_f32_e32 v61, v19, v19
	v_fmac_f32_e32 v87, v20, v20
	v_fmac_f32_e32 v88, v21, v21
	v_fmac_f32_e32 v89, v22, v22
	v_fmac_f32_e32 v90, v23, v23
	v_fmac_f32_e32 v91, v24, v24
	v_fmac_f32_e32 v92, v25, v25
	v_fmac_f32_e32 v93, v26, v26
	v_fmac_f32_e32 v94, v27, v27
	v_fmac_f32_e32 v95, v28, v28
	v_fmac_f32_e32 v96, v29, v29
	v_fmac_f32_e32 v97, v30, v30
	v_fmac_f32_e32 v98, v31, v31
	v_fmac_f32_e32 v99, v32, v32
	v_fmac_f32_e32 v100, v33, v33
	v_add_f32_dpp v57, v57, v57 quad_perm:[2,3,0,1] row_mask:0xf bank_mask:0xf bound_ctrl:1
	v_add_f32_dpp v61, v61, v61 quad_perm:[2,3,0,1] row_mask:0xf bank_mask:0xf bound_ctrl:1
	v_add_f32_dpp v87, v87, v87 quad_perm:[2,3,0,1] row_mask:0xf bank_mask:0xf bound_ctrl:1
	v_add_f32_dpp v88, v88, v88 quad_perm:[2,3,0,1] row_mask:0xf bank_mask:0xf bound_ctrl:1
; __device__ __forceinline__ u16 f2bf(float f) { return (u16)(pack2(f, f) & 0xffffu); }
; __device__ __forceinline__ float sum32(float v) { v = dpp_row_sum16(v); v += __shfl_xor(v, 16); return v; }
; __device__ __forceinline__ int rowmap(int e, int lane) { return (e & 3) + 8 * (e >> 2) + 4 * (lane >> 5); }
; __device__ __forceinline__ void seq_item(const Params& p, int item, char* smem, const bool write_o = true) {
;     ...
;       for (int e = 0; e < 16; e++) {
;         const int t = w * 32 + rowmap(e, lane);
;         if (write_o) Om[(size_t)(tok0 + t) * 512 + h * 128 + sl * 32 + r] = f2bf(o[e]);
;         float sq = sum32(o[e] * o[e]);
;         if (r == 0) SSQO[((size_t)(tok0 + t) * 4 + h) * 4 + sl] = sq;
	v_add_f32_dpp v89, v89, v89 quad_perm:[2,3,0,1] row_mask:0xf bank_mask:0xf bound_ctrl:1
	v_add_f32_dpp v90, v90, v90 quad_perm:[2,3,0,1] row_mask:0xf bank_mask:0xf bound_ctrl:1
	v_add_f32_dpp v91, v91, v91 quad_perm:[2,3,0,1] row_mask:0xf bank_mask:0xf bound_ctrl:1
	v_add_f32_dpp v92, v92, v92 quad_perm:[2,3,0,1] row_mask:0xf bank_mask:0xf bound_ctrl:1
	v_add_f32_dpp v93, v93, v93 quad_perm:[2,3,0,1] row_mask:0xf bank_mask:0xf bound_ctrl:1
	v_add_f32_dpp v94, v94, v94 quad_perm:[2,3,0,1] row_mask:0xf bank_mask:0xf bound_ctrl:1
	v_add_f32_dpp v95, v95, v95 quad_perm:[2,3,0,1] row_mask:0xf bank_mask:0xf bound_ctrl:1
	v_add_f32_dpp v96, v96, v96 quad_perm:[2,3,0,1] row_mask:0xf bank_mask:0xf bound_ctrl:1
	v_add_f32_dpp v97, v97, v97 quad_perm:[2,3,0,1] row_mask:0xf bank_mask:0xf bound_ctrl:1
	v_add_f32_dpp v98, v98, v98 quad_perm:[2,3,0,1] row_mask:0xf bank_mask:0xf bound_ctrl:1
	v_add_f32_dpp v99, v99, v99 quad_perm:[2,3,0,1] row_mask:0xf bank_mask:0xf bound_ctrl:1
	v_add_f32_dpp v100, v100, v100 quad_perm:[2,3,0,1] row_mask:0xf bank_mask:0xf bound_ctrl:1
	v_add_f32_dpp v57, v57, v57 row_half_mirror row_mask:0xf bank_mask:0xf bound_ctrl:1
	v_add_f32_dpp v61, v61, v61 row_half_mirror row_mask:0xf bank_mask:0xf bound_ctrl:1
	v_add_f32_dpp v87, v87, v87 row_half_mirror row_mask:0xf bank_mask:0xf bound_ctrl:1
	v_add_f32_dpp v88, v88, v88 row_half_mirror row_mask:0xf bank_mask:0xf bound_ctrl:1
	v_add_f32_dpp v89, v89, v89 row_half_mirror row_mask:0xf bank_mask:0xf bound_ctrl:1
	v_add_f32_dpp v90, v90, v90 row_half_mirror row_mask:0xf bank_mask:0xf bound_ctrl:1
	v_add_f32_dpp v91, v91, v91 row_half_mirror row_mask:0xf bank_mask:0xf bound_ctrl:1
	v_add_f32_dpp v92, v92, v92 row_half_mirror row_mask:0xf bank_mask:0xf bound_ctrl:1
	v_add_f32_dpp v93, v93, v93 row_half_mirror row_mask:0xf bank_mask:0xf bound_ctrl:1
	v_add_f32_dpp v94, v94, v94 row_half_mirror row_mask:0xf bank_mask:0xf bound_ctrl:1
	v_add_f32_dpp v95, v95, v95 row_half_mirror row_mask:0xf bank_mask:0xf bound_ctrl:1
	v_add_f32_dpp v96, v96, v96 row_half_mirror row_mask:0xf bank_mask:0xf bound_ctrl:1
	v_add_f32_dpp v97, v97, v97 row_half_mirror row_mask:0xf bank_mask:0xf bound_ctrl:1
	v_add_f32_dpp v98, v98, v98 row_half_mirror row_mask:0xf bank_mask:0xf bound_ctrl:1
	v_add_f32_dpp v99, v99, v99 row_half_mirror row_mask:0xf bank_mask:0xf bound_ctrl:1
	v_add_f32_dpp v100, v100, v100 row_half_mirror row_mask:0xf bank_mask:0xf bound_ctrl:1
	v_add_f32_dpp v57, v57, v57 row_mirror row_mask:0xf bank_mask:0xf bound_ctrl:1
	v_add_f32_dpp v61, v61, v61 row_mirror row_mask:0xf bank_mask:0xf bound_ctrl:1
	v_add_f32_dpp v87, v87, v87 row_mirror row_mask:0xf bank_mask:0xf bound_ctrl:1
	v_add_f32_dpp v88, v88, v88 row_mirror row_mask:0xf bank_mask:0xf bound_ctrl:1
	v_add_f32_dpp v89, v89, v89 row_mirror row_mask:0xf bank_mask:0xf bound_ctrl:1
	v_add_f32_dpp v90, v90, v90 row_mirror row_mask:0xf bank_mask:0xf bound_ctrl:1
	v_add_f32_dpp v91, v91, v91 row_mirror row_mask:0xf bank_mask:0xf bound_ctrl:1
	v_add_f32_dpp v92, v92, v92 row_mirror row_mask:0xf bank_mask:0xf bound_ctrl:1
	v_add_f32_dpp v93, v93, v93 row_mirror row_mask:0xf bank_mask:0xf bound_ctrl:1
	v_add_f32_dpp v94, v94, v94 row_mirror row_mask:0xf bank_mask:0xf bound_ctrl:1
	v_add_f32_dpp v95, v95, v95 row_mirror row_mask:0xf bank_mask:0xf bound_ctrl:1
	v_add_f32_dpp v96, v96, v96 row_mirror row_mask:0xf bank_mask:0xf bound_ctrl:1
	v_add_f32_dpp v97, v97, v97 row_mirror row_mask:0xf bank_mask:0xf bound_ctrl:1
	v_add_f32_dpp v98, v98, v98 row_mirror row_mask:0xf bank_mask:0xf bound_ctrl:1
	v_add_f32_dpp v99, v99, v99 row_mirror row_mask:0xf bank_mask:0xf bound_ctrl:1
	v_add_f32_dpp v100, v100, v100 row_mirror row_mask:0xf bank_mask:0xf bound_ctrl:1
	v_mov_b32_e32 v0, v62
	v_lshlrev_b64 v[78:79], 10, v[0:1]
	v_lshl_add_u64 v[78:79], v[70:71], 0, v[78:79]
	v_cvt_pk_bf16_f32 v18, v18, v18
	v_cvt_pk_bf16_f32 v19, v19, v19
	v_cvt_pk_bf16_f32 v20, v20, v20
	v_cvt_pk_bf16_f32 v21, v21, v21
	global_store_short v[78:79], v18, off
	global_store_short v[78:79], v19, off offset:1024
	global_store_short v[78:79], v20, off offset:2048
	global_store_short v[78:79], v21, off offset:3072
	v_or_b32_e32 v0, 8, v62
	v_lshlrev_b64 v[78:79], 10, v[0:1]
	v_lshl_add_u64 v[78:79], v[70:71], 0, v[78:79]
	v_cvt_pk_bf16_f32 v22, v22, v22
	v_cvt_pk_bf16_f32 v23, v23, v23
	v_cvt_pk_bf16_f32 v24, v24, v24
	v_cvt_pk_bf16_f32 v25, v25, v25
	global_store_short v[78:79], v22, off
	global_store_short v[78:79], v23, off offset:1024
	global_store_short v[78:79], v24, off offset:2048
	global_store_short v[78:79], v25, off offset:3072
	v_or_b32_e32 v0, 16, v62
	v_lshlrev_b64 v[78:79], 10, v[0:1]
	v_lshl_add_u64 v[78:79], v[70:71], 0, v[78:79]
	v_cvt_pk_bf16_f32 v26, v26, v26
	v_cvt_pk_bf16_f32 v27, v27, v27
	v_cvt_pk_bf16_f32 v28, v28, v28
	v_cvt_pk_bf16_f32 v29, v29, v29
	global_store_short v[78:79], v26, off
	global_store_short v[78:79], v27, off offset:1024
	global_store_short v[78:79], v28, off offset:2048
	global_store_short v[78:79], v29, off offset:3072
	v_or_b32_e32 v0, 24, v62
	v_lshlrev_b64 v[78:79], 10, v[0:1]
	v_lshl_add_u64 v[78:79], v[70:71], 0, v[78:79]
	v_cvt_pk_bf16_f32 v30, v30, v30
	v_cvt_pk_bf16_f32 v31, v31, v31
	v_cvt_pk_bf16_f32 v32, v32, v32
	v_cvt_pk_bf16_f32 v33, v33, v33
	global_store_short v[78:79], v30, off
	global_store_short v[78:79], v31, off offset:1024
	global_store_short v[78:79], v32, off offset:2048
	global_store_short v[78:79], v33, off offset:3072
	s_nop 0
	ds_bpermute_b32 v18, v63, v57
	ds_bpermute_b32 v19, v63, v61
	ds_bpermute_b32 v20, v63, v87
	ds_bpermute_b32 v21, v63, v88
	ds_bpermute_b32 v22, v63, v89
	ds_bpermute_b32 v23, v63, v90
	ds_bpermute_b32 v24, v63, v91
	ds_bpermute_b32 v25, v63, v92
	ds_bpermute_b32 v26, v63, v93
	ds_bpermute_b32 v27, v63, v94
	ds_bpermute_b32 v28, v63, v95
	ds_bpermute_b32 v29, v63, v96
	s_waitcnt lgkmcnt(8)
; __device__ __forceinline__ void seq_item(const Params& p, int item, char* smem, const bool write_o = true) {
;     ...
;         if (r == 0) SSQO[((size_t)(tok0 + t) * 4 + h) * 4 + sl] = sq;
;       }
;     }
; #pragma unroll
;     for (int e = 0; e < 16; e++) S[e] *= dvn;
; #pragma unroll
;     for (int ks = 0; ks < 4; ks++) {
;       bf16x8 a = *(const bf16x8*)&VTs[r * 72 + ks * 16 + hh];
;       S = mfma16(a, ktf[ks], S);
;     }
;     if (m == 1) {
; #pragma unroll
;       for (int ks = 0; ks < 8; ks++) {
;         bf16x8 a = *(const bf16x8*)&STs[r * 136 + ks * 16 + hh];
;         S = mfma16(a, pnf[ks], S);
;       }
;     }
	ds_bpermute_b32 v30, v63, v97
	ds_bpermute_b32 v31, v63, v98
	ds_bpermute_b32 v32, v63, v99
	ds_bpermute_b32 v33, v63, v100
	s_waitcnt lgkmcnt(0)
	v_add_f32_e32 v57, v57, v18
	v_add_f32_e32 v61, v61, v19
	v_add_f32_e32 v87, v87, v20
	v_add_f32_e32 v88, v88, v21
	v_add_f32_e32 v89, v89, v22
	v_add_f32_e32 v90, v90, v23
	v_add_f32_e32 v91, v91, v24
	v_add_f32_e32 v92, v92, v25
	v_add_f32_e32 v93, v93, v26
	v_add_f32_e32 v94, v94, v27
	v_add_f32_e32 v95, v95, v28
	v_add_f32_e32 v96, v96, v29
	v_add_f32_e32 v97, v97, v30
	v_add_f32_e32 v98, v98, v31
	v_add_f32_e32 v99, v99, v32
	v_add_f32_e32 v100, v100, v33
	s_and_b64 exec, exec, s[8:9]
	v_mov_b32_e32 v0, v62
	v_lshlrev_b64 v[78:79], 6, v[0:1]
	v_lshl_add_u64 v[78:79], s[18:19], 0, v[78:79]
	global_store_dword v[78:79], v57, off
	global_store_dword v[78:79], v61, off offset:64
	global_store_dword v[78:79], v87, off offset:128
	global_store_dword v[78:79], v88, off offset:192
	v_or_b32_e32 v0, 8, v62
	v_lshlrev_b64 v[78:79], 6, v[0:1]
	v_lshl_add_u64 v[78:79], s[18:19], 0, v[78:79]
	global_store_dword v[78:79], v89, off
	global_store_dword v[78:79], v90, off offset:64
	global_store_dword v[78:79], v91, off offset:128
	global_store_dword v[78:79], v92, off offset:192
	v_or_b32_e32 v0, 16, v62
	v_lshlrev_b64 v[78:79], 6, v[0:1]
	v_lshl_add_u64 v[78:79], s[18:19], 0, v[78:79]
	global_store_dword v[78:79], v93, off
	global_store_dword v[78:79], v94, off offset:64
	global_store_dword v[78:79], v95, off offset:128
	global_store_dword v[78:79], v96, off offset:192
	v_or_b32_e32 v0, 24, v62
	v_lshlrev_b64 v[78:79], 6, v[0:1]
	v_lshl_add_u64 v[78:79], s[18:19], 0, v[78:79]
	global_store_dword v[78:79], v97, off
	global_store_dword v[78:79], v98, off offset:64
	global_store_dword v[78:79], v99, off offset:128
	global_store_dword v[78:79], v100, off offset:192
.LBB0_1055:
	s_or_b64 exec, exec, s[0:1]
	s_waitcnt lgkmcnt(0)
	v_pk_mul_f32 v[2:3], v[2:3], v[58:59] op_sel_hi:[1,0]
	v_pk_mul_f32 v[16:17], v[16:17], v[58:59] op_sel_hi:[1,0]
	v_pk_mul_f32 v[14:15], v[14:15], v[58:59] op_sel_hi:[1,0]
	v_pk_mul_f32 v[12:13], v[12:13], v[58:59] op_sel_hi:[1,0]
	v_pk_mul_f32 v[10:11], v[10:11], v[58:59] op_sel_hi:[1,0]
	v_pk_mul_f32 v[8:9], v[8:9], v[58:59] op_sel_hi:[1,0]
	v_pk_mul_f32 v[6:7], v[6:7], v[58:59] op_sel_hi:[1,0]
	v_pk_mul_f32 v[4:5], v[4:5], v[58:59] op_sel_hi:[1,0]
	v_cndmask_b32_e64 v0, 0, 1, s[16:17]
	v_accvgpr_write_b32 a0, v2
	v_accvgpr_write_b32 a1, v3
	v_accvgpr_write_b32 a2, v4
	v_accvgpr_write_b32 a3, v5
	v_accvgpr_write_b32 a4, v6
	v_accvgpr_write_b32 a5, v7
	v_accvgpr_write_b32 a6, v8
	v_accvgpr_write_b32 a7, v9
	v_accvgpr_write_b32 a8, v10
	v_accvgpr_write_b32 a9, v11
	v_accvgpr_write_b32 a10, v12
	v_accvgpr_write_b32 a11, v13
	v_accvgpr_write_b32 a12, v14
	v_accvgpr_write_b32 a13, v15
	v_accvgpr_write_b32 a14, v16
	v_accvgpr_write_b32 a15, v17
	s_nop 1
	v_mfma_f32_32x32x16_bf16 a[0:15], v[188:191], v[106:109], a[0:15]
	v_cmp_ne_u32_e64 s[0:1], 1, v0
	s_andn2_b64 vcc, exec, s[16:17]
	v_mfma_f32_32x32x16_bf16 a[0:15], v[224:227], v[110:113], a[0:15]
	v_mfma_f32_32x32x16_bf16 a[0:15], v[228:231], v[114:117], a[0:15]
	v_mfma_f32_32x32x16_bf16 a[0:15], v[242:245], v[118:121], a[0:15]
	s_cbranch_vccnz .LBB0_1057
	v_mfma_f32_32x32x16_bf16 a[0:15], v[192:195], v[122:125], a[0:15]
	v_mfma_f32_32x32x16_bf16 a[0:15], v[196:199], v[126:129], a[0:15]
	v_mfma_f32_32x32x16_bf16 a[0:15], v[200:203], v[130:133], a[0:15]
	v_mfma_f32_32x32x16_bf16 a[0:15], v[204:207], v[134:137], a[0:15]
	v_mfma_f32_32x32x16_bf16 a[0:15], v[208:211], v[138:141], a[0:15]
	v_mfma_f32_32x32x16_bf16 a[0:15], v[212:215], v[142:145], a[0:15]
	v_mfma_f32_32x32x16_bf16 a[0:15], v[216:219], v[146:149], a[0:15]
	v_mfma_f32_32x32x16_bf16 a[0:15], v[220:223], v[150:153], a[0:15]

; __device__ __forceinline__ void convert_item_fp8(const float* __restrict__ src, unsigned char* __restrict__ dst, size_t item, float scale) {
;   size_t base = item * 8192 + (size_t)threadIdx.x * 16;
;   float4 a[2][4];
; #pragma unroll
;   for (int i = 0; i < 2; i++) {
;     const float4* q = (const float4*)(src + base + i * 4096);
; #pragma unroll
;     for (int j = 0; j < 4; j++) a[i][j] = q[j];
;   }
; #pragma unroll
;   for (int i = 0; i < 2; i++) {
;     unsigned o[4];
; #pragma unroll
;     for (int j = 0; j < 4; j++) {
;       int pk = __builtin_amdgcn_cvt_pk_fp8_f32(a[i][j].x * scale, a[i][j].y * scale, 0, false);
;       pk = __builtin_amdgcn_cvt_pk_fp8_f32(a[i][j].z * scale, a[i][j].w * scale, pk, true);
;       o[j] = (unsigned)pk;
;     }
;     *(uint4*)(dst + base + i * 4096) = make_uint4(o[0], o[1], o[2], o[3]);
;   }
; }
; __device__ __forceinline__ void phase4a(const Params& p, char* smem) {
;     ...
;     const int extra = split_ok ? 2 * nleft : nleft;
;     int first = bx - extra, stride = G - extra;
;     if (stride <= 0) { first = bx; stride = G; }
;     if (first >= 0) {
; #pragma unroll 1
;       for (int ci = first; ci < NCONV; ci += stride) {
;         if (ci < 2048) convert_item_fp8(p.expert_u, (unsigned char*)(ws + OFF_EU), ci, EU_SCALE);
;         else convert_item_fp8(p.expert_v, (unsigned char*)(ws + OFF_EV), ci - 2048, EV_SCALE);
;       }
;     }
.LBB0_1176:
	s_and_b64 s[0:1], s[4:5], exec
	s_cselect_b32 s0, s13, s55
	s_sub_i32 s1, s82, s0
	s_cmp_lt_i32 s1, 1
	s_cselect_b64 s[6:7], -1, 0
	s_and_b64 s[4:5], s[6:7], exec
	s_cselect_b32 s0, 0, s0
	s_sub_i32 s0, s96, s0
	s_cmpk_gt_u32 s0, 0xfff
	s_mov_b32 s5, 0
	v_readlane_b32 s74, v254, 35
	v_accvgpr_read_b32 v182, a132
	s_cbranch_scc1 .LBB0_1182
	s_and_b64 s[6:7], s[6:7], exec
	s_cselect_b32 s14, s82, s1
	v_accvgpr_write_b32 a139, 0
	v_readlane_b32 s66, v254, 29
	v_readlane_b32 s67, v254, 30
	v_readlane_b32 s68, v254, 31
	v_readlane_b32 s69, v254, 32
	v_accvgpr_read_b32 v40, a138
	s_nop 0
	v_lshlrev_b32_e32 v41, 2, v40
	v_and_b32_e32 v42, 0x380, v40
	v_lshlrev_b32_e32 v42, 14, v42
	v_lshrrev_b32_e32 v43, 3, v40
	v_and_b32_e32 v43, 0x180, v43
	v_and_b32_e32 v40, 0x7f, v40
	v_or3_b32 v42, v40, v42, v43
	s_mov_b32 s15, 0x41800000
	s_mov_b32 s16, 0xbf35000
.Lcv_top:
	s_mov_b32 s4, s0
	s_min_u32 s5, s4, 0xfff
	s_cmpk_lt_u32 s5, 0x800
	s_cselect_b32 s56, s66, s68
	s_cselect_b32 s57, s67, s69
	s_cselect_b32 s8, 0x42800000, s15
	s_cselect_b32 s7, 0xaf35000, s16
	s_and_b32 s5, s5, 0x7ff
	s_lshl_b32 s6, s5, 15
	v_add_u32_e32 v184, s6, v41
	v_add_u32_e32 v188, 0x4000, v184
	s_lshl_b32 s6, s5, 10
	s_add_u32 s6, s6, s7
	v_add_u32_e32 v192, s6, v42
	global_load_dwordx4 v[44:47], v184, s[56:57]
	global_load_dwordx4 v[48:51], v184, s[56:57] offset:16
	global_load_dwordx4 v[52:55], v184, s[56:57] offset:32
	global_load_dwordx4 v[56:59], v184, s[56:57] offset:48
	global_load_dwordx4 v[60:63], v188, s[56:57]
	global_load_dwordx4 v[64:67], v188, s[56:57] offset:16
	global_load_dwordx4 v[68:71], v188, s[56:57] offset:32
	global_load_dwordx4 v[72:75], v188, s[56:57] offset:48
	s_mul_i32 s4, s14, 1
	s_add_i32 s4, s0, s4
	s_min_u32 s5, s4, 0xfff
	s_cmpk_lt_u32 s5, 0x800
	s_cselect_b32 s58, s66, s68
	s_cselect_b32 s59, s67, s69
	s_cselect_b32 s9, 0x42800000, s15
	s_cselect_b32 s7, 0xaf35000, s16
	s_and_b32 s5, s5, 0x7ff
	s_lshl_b32 s6, s5, 15
	v_add_u32_e32 v185, s6, v41
	v_add_u32_e32 v189, 0x4000, v185
	s_lshl_b32 s6, s5, 10
	s_add_u32 s6, s6, s7
	v_add_u32_e32 v193, s6, v42
	global_load_dwordx4 v[76:79], v185, s[58:59]
	global_load_dwordx4 v[80:83], v185, s[58:59] offset:16
	global_load_dwordx4 v[84:87], v185, s[58:59] offset:32
	global_load_dwordx4 v[88:91], v185, s[58:59] offset:48
	global_load_dwordx4 v[92:95], v189, s[58:59]
	global_load_dwordx4 v[96:99], v189, s[58:59] offset:16
	global_load_dwordx4 v[100:103], v189, s[58:59] offset:32
	global_load_dwordx4 v[104:107], v189, s[58:59] offset:48
	s_mul_i32 s4, s14, 2
	s_add_i32 s4, s0, s4
	s_min_u32 s5, s4, 0xfff
	s_cmpk_lt_u32 s5, 0x800
	s_cselect_b32 s60, s66, s68
	s_cselect_b32 s61, s67, s69
	s_cselect_b32 s10, 0x42800000, s15
	s_cselect_b32 s7, 0xaf35000, s16
	s_and_b32 s5, s5, 0x7ff
	s_lshl_b32 s6, s5, 15
	v_add_u32_e32 v186, s6, v41
	v_add_u32_e32 v190, 0x4000, v186
	s_lshl_b32 s6, s5, 10
	s_add_u32 s6, s6, s7
	v_add_u32_e32 v194, s6, v42
	global_load_dwordx4 v[108:111], v186, s[60:61]
	global_load_dwordx4 v[112:115], v186, s[60:61] offset:16
	global_load_dwordx4 v[116:119], v186, s[60:61] offset:32
	global_load_dwordx4 v[120:123], v186, s[60:61] offset:48
	global_load_dwordx4 v[124:127], v190, s[60:61]
	global_load_dwordx4 v[128:131], v190, s[60:61] offset:16
	global_load_dwordx4 v[132:135], v190, s[60:61] offset:32
	global_load_dwordx4 v[136:139], v190, s[60:61] offset:48
	s_mul_i32 s4, s14, 3
	s_add_i32 s4, s0, s4
	s_min_u32 s5, s4, 0xfff
	s_cmpk_lt_u32 s5, 0x800
	s_cselect_b32 s62, s66, s68
	s_cselect_b32 s63, s67, s69
	s_cselect_b32 s11, 0x42800000, s15
	s_cselect_b32 s7, 0xaf35000, s16
	s_and_b32 s5, s5, 0x7ff
	s_lshl_b32 s6, s5, 15
	v_add_u32_e32 v187, s6, v41
	v_add_u32_e32 v191, 0x4000, v187
	s_lshl_b32 s6, s5, 10
	s_add_u32 s6, s6, s7
	v_add_u32_e32 v195, s6, v42
	global_load_dwordx4 v[140:143], v187, s[62:63]
	global_load_dwordx4 v[144:147], v187, s[62:63] offset:16
	global_load_dwordx4 v[148:151], v187, s[62:63] offset:32
	global_load_dwordx4 v[152:155], v187, s[62:63] offset:48
	global_load_dwordx4 v[156:159], v191, s[62:63]
	global_load_dwordx4 v[160:163], v191, s[62:63] offset:16
	global_load_dwordx4 v[164:167], v191, s[62:63] offset:32
	global_load_dwordx4 v[168:171], v191, s[62:63] offset:48
	s_mov_b32 s4, s0
	s_cmpk_gt_u32 s4, 0xfff
	s_cbranch_scc1 .Lcv_done
	s_waitcnt vmcnt(24)
	v_mul_f32_e32 v44, s8, v44
	v_mul_f32_e32 v45, s8, v45
	v_mul_f32_e32 v46, s8, v46
	v_mul_f32_e32 v47, s8, v47
	v_mul_f32_e32 v48, s8, v48
	v_mul_f32_e32 v49, s8, v49
	v_mul_f32_e32 v50, s8, v50
	v_mul_f32_e32 v51, s8, v51
	v_mul_f32_e32 v52, s8, v52
	v_mul_f32_e32 v53, s8, v53
	v_mul_f32_e32 v54, s8, v54
	v_mul_f32_e32 v55, s8, v55
	v_mul_f32_e32 v56, s8, v56
	v_mul_f32_e32 v57, s8, v57
	v_mul_f32_e32 v58, s8, v58
	v_mul_f32_e32 v59, s8, v59
	v_mul_f32_e32 v60, s8, v60
	v_mul_f32_e32 v61, s8, v61
	v_mul_f32_e32 v62, s8, v62
	v_mul_f32_e32 v63, s8, v63
	v_mul_f32_e32 v64, s8, v64
	v_mul_f32_e32 v65, s8, v65
	v_mul_f32_e32 v66, s8, v66
	v_mul_f32_e32 v67, s8, v67
	v_mul_f32_e32 v68, s8, v68
	v_mul_f32_e32 v69, s8, v69
	v_mul_f32_e32 v70, s8, v70
	v_mul_f32_e32 v71, s8, v71
	v_mul_f32_e32 v72, s8, v72
	v_mul_f32_e32 v73, s8, v73
	v_mul_f32_e32 v74, s8, v74
	v_mul_f32_e32 v75, s8, v75
	v_cvt_pk_fp8_f32 v32, v44, v45
	v_cvt_pk_fp8_f32 v33, v48, v49
	v_cvt_pk_fp8_f32 v34, v52, v53
	v_cvt_pk_fp8_f32 v35, v56, v57
	v_cvt_pk_fp8_f32 v36, v60, v61
	v_cvt_pk_fp8_f32 v37, v64, v65
	v_cvt_pk_fp8_f32 v38, v68, v69
	v_cvt_pk_fp8_f32 v39, v72, v73
	v_cvt_pk_fp8_f32 v32, v46, v47 op_sel:[0,0,1]
	v_cvt_pk_fp8_f32 v33, v50, v51 op_sel:[0,0,1]
	v_cvt_pk_fp8_f32 v34, v54, v55 op_sel:[0,0,1]
	v_cvt_pk_fp8_f32 v35, v58, v59 op_sel:[0,0,1]
	v_cvt_pk_fp8_f32 v36, v62, v63 op_sel:[0,0,1]
	v_cvt_pk_fp8_f32 v37, v66, v67 op_sel:[0,0,1]
	v_cvt_pk_fp8_f32 v38, v70, v71 op_sel:[0,0,1]
	v_cvt_pk_fp8_f32 v39, v74, v75 op_sel:[0,0,1]
	s_nop 0
	global_store_dwordx4 v192, v[32:35], s[80:81]
	global_store_dwordx4 v192, v[36:39], s[80:81] offset:512
	s_mul_i32 s4, s14, 1
	s_add_i32 s4, s0, s4
	s_cmpk_gt_u32 s4, 0xfff
	s_cbranch_scc1 .Lcv_done
; __device__ __forceinline__ void convert_item_fp8(const float* __restrict__ src, unsigned char* __restrict__ dst, size_t item, float scale) {
;   size_t base = item * 8192 + (size_t)threadIdx.x * 16;
;   float4 a[2][4];
; #pragma unroll
;   for (int i = 0; i < 2; i++) {
;     const float4* q = (const float4*)(src + base + i * 4096);
; #pragma unroll
;     for (int j = 0; j < 4; j++) a[i][j] = q[j];
;   }
; #pragma unroll
;   for (int i = 0; i < 2; i++) {
;     unsigned o[4];
; #pragma unroll
;     for (int j = 0; j < 4; j++) {
;       int pk = __builtin_amdgcn_cvt_pk_fp8_f32(a[i][j].x * scale, a[i][j].y * scale, 0, false);
;       pk = __builtin_amdgcn_cvt_pk_fp8_f32(a[i][j].z * scale, a[i][j].w * scale, pk, true);
;       o[j] = (unsigned)pk;
;     }
;     *(uint4*)(dst + base + i * 4096) = make_uint4(o[0], o[1], o[2], o[3]);
;   }
; }
; __device__ __forceinline__ void phase4a(const Params& p, char* smem) {
;     ...
;     const int extra = split_ok ? 2 * nleft : nleft;
;     int first = bx - extra, stride = G - extra;
;     if (stride <= 0) { first = bx; stride = G; }
;     if (first >= 0) {
; #pragma unroll 1
;       for (int ci = first; ci < NCONV; ci += stride) {
;         if (ci < 2048) convert_item_fp8(p.expert_u, (unsigned char*)(ws + OFF_EU), ci, EU_SCALE);
;         else convert_item_fp8(p.expert_v, (unsigned char*)(ws + OFF_EV), ci - 2048, EV_SCALE);
;       }
;     }
	s_waitcnt vmcnt(18)
	v_mul_f32_e32 v76, s9, v76
	v_mul_f32_e32 v77, s9, v77
	v_mul_f32_e32 v78, s9, v78
	v_mul_f32_e32 v79, s9, v79
	v_mul_f32_e32 v80, s9, v80
	v_mul_f32_e32 v81, s9, v81
	v_mul_f32_e32 v82, s9, v82
	v_mul_f32_e32 v83, s9, v83
	v_mul_f32_e32 v84, s9, v84
	v_mul_f32_e32 v85, s9, v85
	v_mul_f32_e32 v86, s9, v86
	v_mul_f32_e32 v87, s9, v87
	v_mul_f32_e32 v88, s9, v88
	v_mul_f32_e32 v89, s9, v89
	v_mul_f32_e32 v90, s9, v90
	v_mul_f32_e32 v91, s9, v91
	v_mul_f32_e32 v92, s9, v92
	v_mul_f32_e32 v93, s9, v93
	v_mul_f32_e32 v94, s9, v94
	v_mul_f32_e32 v95, s9, v95
	v_mul_f32_e32 v96, s9, v96
	v_mul_f32_e32 v97, s9, v97
	v_mul_f32_e32 v98, s9, v98
	v_mul_f32_e32 v99, s9, v99
	v_mul_f32_e32 v100, s9, v100
	v_mul_f32_e32 v101, s9, v101
	v_mul_f32_e32 v102, s9, v102
	v_mul_f32_e32 v103, s9, v103
	v_mul_f32_e32 v104, s9, v104
	v_mul_f32_e32 v105, s9, v105
	v_mul_f32_e32 v106, s9, v106
	v_mul_f32_e32 v107, s9, v107
	v_cvt_pk_fp8_f32 v196, v76, v77
	v_cvt_pk_fp8_f32 v197, v80, v81
	v_cvt_pk_fp8_f32 v198, v84, v85
	v_cvt_pk_fp8_f32 v199, v88, v89
	v_cvt_pk_fp8_f32 v200, v92, v93
	v_cvt_pk_fp8_f32 v201, v96, v97
	v_cvt_pk_fp8_f32 v202, v100, v101
	v_cvt_pk_fp8_f32 v203, v104, v105
	v_cvt_pk_fp8_f32 v196, v78, v79 op_sel:[0,0,1]
	v_cvt_pk_fp8_f32 v197, v82, v83 op_sel:[0,0,1]
	v_cvt_pk_fp8_f32 v198, v86, v87 op_sel:[0,0,1]
	v_cvt_pk_fp8_f32 v199, v90, v91 op_sel:[0,0,1]
	v_cvt_pk_fp8_f32 v200, v94, v95 op_sel:[0,0,1]
	v_cvt_pk_fp8_f32 v201, v98, v99 op_sel:[0,0,1]
	v_cvt_pk_fp8_f32 v202, v102, v103 op_sel:[0,0,1]
	v_cvt_pk_fp8_f32 v203, v106, v107 op_sel:[0,0,1]
	s_nop 0
	global_store_dwordx4 v193, v[196:199], s[80:81]
	global_store_dwordx4 v193, v[200:203], s[80:81] offset:512
	s_mul_i32 s4, s14, 2
	s_add_i32 s4, s0, s4
	s_cmpk_gt_u32 s4, 0xfff
	s_cbranch_scc1 .Lcv_done
	s_waitcnt vmcnt(12)
	v_mul_f32_e32 v108, s10, v108
	v_mul_f32_e32 v109, s10, v109
	v_mul_f32_e32 v110, s10, v110
	v_mul_f32_e32 v111, s10, v111
	v_mul_f32_e32 v112, s10, v112
	v_mul_f32_e32 v113, s10, v113
	v_mul_f32_e32 v114, s10, v114
	v_mul_f32_e32 v115, s10, v115
	v_mul_f32_e32 v116, s10, v116
	v_mul_f32_e32 v117, s10, v117
	v_mul_f32_e32 v118, s10, v118
	v_mul_f32_e32 v119, s10, v119
	v_mul_f32_e32 v120, s10, v120
	v_mul_f32_e32 v121, s10, v121
	v_mul_f32_e32 v122, s10, v122
	v_mul_f32_e32 v123, s10, v123
	v_mul_f32_e32 v124, s10, v124
	v_mul_f32_e32 v125, s10, v125
	v_mul_f32_e32 v126, s10, v126
	v_mul_f32_e32 v127, s10, v127
	v_mul_f32_e32 v128, s10, v128
	v_mul_f32_e32 v129, s10, v129
	v_mul_f32_e32 v130, s10, v130
	v_mul_f32_e32 v131, s10, v131
	v_mul_f32_e32 v132, s10, v132
	v_mul_f32_e32 v133, s10, v133
	v_mul_f32_e32 v134, s10, v134
	v_mul_f32_e32 v135, s10, v135
	v_mul_f32_e32 v136, s10, v136
	v_mul_f32_e32 v137, s10, v137
	v_mul_f32_e32 v138, s10, v138
	v_mul_f32_e32 v139, s10, v139
	v_cvt_pk_fp8_f32 v32, v108, v109
	v_cvt_pk_fp8_f32 v33, v112, v113
	v_cvt_pk_fp8_f32 v34, v116, v117
	v_cvt_pk_fp8_f32 v35, v120, v121
	v_cvt_pk_fp8_f32 v36, v124, v125
	v_cvt_pk_fp8_f32 v37, v128, v129
	v_cvt_pk_fp8_f32 v38, v132, v133
	v_cvt_pk_fp8_f32 v39, v136, v137
	v_cvt_pk_fp8_f32 v32, v110, v111 op_sel:[0,0,1]
	v_cvt_pk_fp8_f32 v33, v114, v115 op_sel:[0,0,1]
	v_cvt_pk_fp8_f32 v34, v118, v119 op_sel:[0,0,1]
	v_cvt_pk_fp8_f32 v35, v122, v123 op_sel:[0,0,1]
	v_cvt_pk_fp8_f32 v36, v126, v127 op_sel:[0,0,1]
	v_cvt_pk_fp8_f32 v37, v130, v131 op_sel:[0,0,1]
	v_cvt_pk_fp8_f32 v38, v134, v135 op_sel:[0,0,1]
	v_cvt_pk_fp8_f32 v39, v138, v139 op_sel:[0,0,1]
	s_nop 0
	global_store_dwordx4 v194, v[32:35], s[80:81]
	global_store_dwordx4 v194, v[36:39], s[80:81] offset:512
	s_mul_i32 s4, s14, 3
	s_add_i32 s4, s0, s4
	s_cmpk_gt_u32 s4, 0xfff
	s_cbranch_scc1 .Lcv_done
	s_waitcnt vmcnt(6)
	v_mul_f32_e32 v140, s11, v140
	v_mul_f32_e32 v141, s11, v141
	v_mul_f32_e32 v142, s11, v142
	v_mul_f32_e32 v143, s11, v143
	v_mul_f32_e32 v144, s11, v144
	v_mul_f32_e32 v145, s11, v145
	v_mul_f32_e32 v146, s11, v146
	v_mul_f32_e32 v147, s11, v147
	v_mul_f32_e32 v148, s11, v148
	v_mul_f32_e32 v149, s11, v149
	v_mul_f32_e32 v150, s11, v150
	v_mul_f32_e32 v151, s11, v151
	v_mul_f32_e32 v152, s11, v152
	v_mul_f32_e32 v153, s11, v153
	v_mul_f32_e32 v154, s11, v154
	v_mul_f32_e32 v155, s11, v155
	v_mul_f32_e32 v156, s11, v156
	v_mul_f32_e32 v157, s11, v157
	v_mul_f32_e32 v158, s11, v158
	v_mul_f32_e32 v159, s11, v159
	v_mul_f32_e32 v160, s11, v160
	v_mul_f32_e32 v161, s11, v161
	v_mul_f32_e32 v162, s11, v162
	v_mul_f32_e32 v163, s11, v163
	v_mul_f32_e32 v164, s11, v164
	v_mul_f32_e32 v165, s11, v165
	v_mul_f32_e32 v166, s11, v166
	v_mul_f32_e32 v167, s11, v167
	v_mul_f32_e32 v168, s11, v168
	v_mul_f32_e32 v169, s11, v169
	v_mul_f32_e32 v170, s11, v170
	v_mul_f32_e32 v171, s11, v171
	v_cvt_pk_fp8_f32 v196, v140, v141
	v_cvt_pk_fp8_f32 v197, v144, v145
	v_cvt_pk_fp8_f32 v198, v148, v149
	v_cvt_pk_fp8_f32 v199, v152, v153
	v_cvt_pk_fp8_f32 v200, v156, v157
	v_cvt_pk_fp8_f32 v201, v160, v161
	v_cvt_pk_fp8_f32 v202, v164, v165
	v_cvt_pk_fp8_f32 v203, v168, v169
	v_cvt_pk_fp8_f32 v196, v142, v143 op_sel:[0,0,1]
	v_cvt_pk_fp8_f32 v197, v146, v147 op_sel:[0,0,1]
	v_cvt_pk_fp8_f32 v198, v150, v151 op_sel:[0,0,1]
	v_cvt_pk_fp8_f32 v199, v154, v155 op_sel:[0,0,1]
	v_cvt_pk_fp8_f32 v200, v158, v159 op_sel:[0,0,1]
	v_cvt_pk_fp8_f32 v201, v162, v163 op_sel:[0,0,1]
	v_cvt_pk_fp8_f32 v202, v166, v167 op_sel:[0,0,1]
	v_cvt_pk_fp8_f32 v203, v170, v171 op_sel:[0,0,1]
	s_nop 0
	global_store_dwordx4 v195, v[196:199], s[80:81]
	global_store_dwordx4 v195, v[200:203], s[80:81] offset:512
	s_mul_i32 s4, s14, 4
	s_add_i32 s0, s0, s4
	s_cmpk_lt_u32 s0, 0x1000
	s_cbranch_scc1 .Lcv_top
.Lcv_done:
.LBB0_1182:
	s_waitcnt vmcnt(0)
	s_waitcnt lgkmcnt(0)
	s_barrier
	s_and_saveexec_b64 s[0:1], s[72:73]
	s_cbranch_execz .LBB0_1234
	v_mov_b32_e32 v0, 0x23800
	s_waitcnt vmcnt(0) expcnt(0) lgkmcnt(0)
	ds_read_b32 v2, v0
	v_mov_b32_e32 v0, 0x23804
	ds_read_b32 v0, v0
	s_waitcnt lgkmcnt(1)
	v_cmp_ne_u32_e32 vcc, 0, v2
	s_cbranch_vccnz .LBB0_1198
	v_readlane_b32 s4, v254, 0
	s_mul_i32 s60, s83, s4
	s_add_u32 s4, s80, 0x12f35200
	s_addc_u32 s5, s81, 0
	s_add_u32 s6, s80, 0x12f35400
	s_addc_u32 s7, s81, 0
	s_add_u32 s8, s80, 0x12f35500
	s_addc_u32 s9, s81, 0
	s_add_u32 s10, s80, 0x12f35600
	s_addc_u32 s11, s81, 0
	s_add_u32 s12, s80, 0x12f35700
	s_addc_u32 s13, s81, 0
	s_add_u32 s14, s80, 0x12f35800
	s_addc_u32 s15, s81, 0
	s_add_u32 s16, s80, 0x12f35900
	s_addc_u32 s17, s81, 0
	s_add_u32 s18, s80, 0x12f35a00
	s_addc_u32 s19, s81, 0
	s_add_u32 s20, s80, 0x12f35b00
	s_addc_u32 s21, s81, 0
	s_add_u32 s22, s80, 0x12f35c00
	s_addc_u32 s23, s81, 0
	s_add_u32 s24, s80, 0x12f35d00
	s_addc_u32 s25, s81, 0
	s_add_u32 s26, s80, 0x12f35e00
	s_addc_u32 s27, s81, 0
	s_add_u32 s28, s80, 0x12f35f00
	s_addc_u32 s29, s81, 0
	s_add_u32 s30, s80, 0x12f36000
	s_addc_u32 s31, s81, 0
	s_add_u32 s34, s80, 0x12f36100
	s_addc_u32 s35, s81, 0
	s_add_u32 s36, s80, 0x12f36200
	s_addc_u32 s37, s81, 0
	s_add_u32 s38, s80, 0x12f36300
	s_mul_i32 s60, s60, s82
	s_addc_u32 s39, s81, 0
	s_mov_b32 s61, 1
	v_mov_b32_e32 v16, 0
	s_branch .LBB0_1186

; __device__ __forceinline__ int rowmap(int e, int lane) { return (e & 3) + 8 * (e >> 2) + 4 * (lane >> 5); }
; __device__ __forceinline__ void phase4b(const Params& p, char* smem) {
;     ...
; #pragma unroll
;     for (int i = 0; i < 2; i++)
; #pragma unroll
;       for (int e = 0; e < 16; e++) {
;         const int row = m0 + wm * 64 + i * 32 + rowmap(e, lane);
;         const float* xr = xrow(p, row);
;         float sq = 0.f;
; #pragma unroll
;         for (int j = 0; j < 2; j++) {
;           const int col = n0 + wn * 64 + j * 32 + (lane & 31);
;           float v = acc[i][j][e] + xr[col];
.LBB0_1297:
	s_waitcnt vmcnt(0)
	s_nop 7
	v_accvgpr_read_b32 v48, a48
	v_accvgpr_read_b32 v49, a49
	v_accvgpr_read_b32 v50, a50
	v_accvgpr_read_b32 v51, a51
	v_accvgpr_read_b32 v52, a52
	v_accvgpr_read_b32 v53, a53
	v_accvgpr_read_b32 v54, a54
	v_accvgpr_read_b32 v55, a55
	v_accvgpr_read_b32 v56, a56
	v_accvgpr_read_b32 v57, a57
	v_accvgpr_read_b32 v58, a58
	v_accvgpr_read_b32 v59, a59
	v_accvgpr_read_b32 v60, a60
	v_accvgpr_read_b32 v61, a61
	v_accvgpr_read_b32 v62, a62
	v_accvgpr_read_b32 v63, a63
	v_accvgpr_read_b32 v32, a32
	v_accvgpr_read_b32 v33, a33
	v_accvgpr_read_b32 v34, a34
	v_accvgpr_read_b32 v35, a35
	v_accvgpr_read_b32 v36, a36
	v_accvgpr_read_b32 v37, a37
	v_accvgpr_read_b32 v38, a38
	v_accvgpr_read_b32 v39, a39
	v_accvgpr_read_b32 v40, a40
	v_accvgpr_read_b32 v41, a41
	v_accvgpr_read_b32 v42, a42
	v_accvgpr_read_b32 v43, a43
	v_accvgpr_read_b32 v44, a44
	v_accvgpr_read_b32 v45, a45
	v_accvgpr_read_b32 v46, a46
	v_accvgpr_read_b32 v47, a47
	v_accvgpr_read_b32 v16, a16
	v_accvgpr_read_b32 v17, a17
	v_accvgpr_read_b32 v18, a18
	v_accvgpr_read_b32 v19, a19
	v_accvgpr_read_b32 v20, a20
	v_accvgpr_read_b32 v21, a21
	v_accvgpr_read_b32 v22, a22
	v_accvgpr_read_b32 v23, a23
	v_accvgpr_read_b32 v24, a24
	v_accvgpr_read_b32 v25, a25
	v_accvgpr_read_b32 v26, a26
	v_accvgpr_read_b32 v27, a27
	v_accvgpr_read_b32 v28, a28
	v_accvgpr_read_b32 v29, a29
	v_accvgpr_read_b32 v30, a30
	v_accvgpr_read_b32 v31, a31
	v_accvgpr_read_b32 v0, a0
	v_accvgpr_read_b32 v1, a1
	v_accvgpr_read_b32 v2, a2
	v_accvgpr_read_b32 v3, a3
	v_accvgpr_read_b32 v4, a4
	v_accvgpr_read_b32 v5, a5
	v_accvgpr_read_b32 v6, a6
	v_accvgpr_read_b32 v7, a7
	v_accvgpr_read_b32 v8, a8
	v_accvgpr_read_b32 v9, a9
	v_accvgpr_read_b32 v10, a10
	v_accvgpr_read_b32 v11, a11
	v_accvgpr_read_b32 v12, a12
	v_accvgpr_read_b32 v13, a13
	v_accvgpr_read_b32 v14, a14
	v_accvgpr_read_b32 v15, a15
	v_add_u32_e32 v135, s6, v105
	v_or_b32_e32 v94, v135, v117
	v_cmp_le_i32_e32 vcc, s14, v94
	v_mov_b32_e32 v64, s42
	v_mov_b32_e32 v137, s40
	v_mov_b32_e32 v95, 0
	v_cndmask_b32_e32 v146, v137, v64, vcc
	v_mov_b32_e32 v64, s43
	v_mov_b32_e32 v137, s41
	v_or_b32_e32 v148, 32, v135
	v_cndmask_b32_e32 v147, v137, v64, vcc
	v_mov_b32_e32 v64, 0xfc000000
	v_cndmask_b32_e32 v92, 0, v64, vcc
	v_cndmask_b32_e64 v93, 0, -1, vcc
	v_lshl_add_u64 v[146:147], v[92:93], 0, v[146:147]
	v_or_b32_e32 v64, s45, v107
	v_lshlrev_b32_e32 v64, 2, v64
	v_lshl_add_u64 v[146:147], v[64:65], 0, v[146:147]
	v_add_lshl_u32 v94, v135, v117, 12
	v_lshl_add_u64 v[92:93], v[94:95], 0, v[146:147]
	global_load_dword a48, v[92:93], off
	global_load_dword a32, v[92:93], off offset:128
	v_add_lshl_u32 v94, v135, v120, 12
	v_lshl_add_u64 v[92:93], v[94:95], 0, v[146:147]
	global_load_dword a49, v[92:93], off
	global_load_dword a33, v[92:93], off offset:128
	v_add_lshl_u32 v94, v135, v121, 12
	v_lshl_add_u64 v[92:93], v[94:95], 0, v[146:147]
	global_load_dword a50, v[92:93], off
	global_load_dword a34, v[92:93], off offset:128
	v_add_lshl_u32 v94, v135, v122, 12
	v_lshl_add_u64 v[92:93], v[94:95], 0, v[146:147]
	global_load_dword a51, v[92:93], off
	global_load_dword a35, v[92:93], off offset:128
	v_add_lshl_u32 v94, v135, v123, 12
	v_lshl_add_u64 v[92:93], v[94:95], 0, v[146:147]
	global_load_dword a52, v[92:93], off
	global_load_dword a36, v[92:93], off offset:128
	v_add_lshl_u32 v94, v135, v124, 12
	v_lshl_add_u64 v[92:93], v[94:95], 0, v[146:147]
	global_load_dword a53, v[92:93], off
	global_load_dword a37, v[92:93], off offset:128
	v_add_lshl_u32 v94, v135, v125, 12
	v_lshl_add_u64 v[92:93], v[94:95], 0, v[146:147]
	global_load_dword a54, v[92:93], off
	global_load_dword a38, v[92:93], off offset:128
	v_add_lshl_u32 v94, v135, v126, 12
	v_lshl_add_u64 v[92:93], v[94:95], 0, v[146:147]
	global_load_dword a55, v[92:93], off
	global_load_dword a39, v[92:93], off offset:128
	v_add_lshl_u32 v94, v135, v127, 12
	v_lshl_add_u64 v[92:93], v[94:95], 0, v[146:147]
	global_load_dword a56, v[92:93], off
	global_load_dword a40, v[92:93], off offset:128
	v_add_lshl_u32 v94, v135, v128, 12
	v_lshl_add_u64 v[92:93], v[94:95], 0, v[146:147]
	global_load_dword a57, v[92:93], off
	global_load_dword a41, v[92:93], off offset:128
	v_add_lshl_u32 v94, v135, v129, 12
	v_lshl_add_u64 v[92:93], v[94:95], 0, v[146:147]
	global_load_dword a58, v[92:93], off
	global_load_dword a42, v[92:93], off offset:128
	v_add_lshl_u32 v94, v135, v130, 12
	v_lshl_add_u64 v[92:93], v[94:95], 0, v[146:147]
	global_load_dword a59, v[92:93], off
	global_load_dword a43, v[92:93], off offset:128
	v_add_lshl_u32 v94, v135, v131, 12
	v_lshl_add_u64 v[92:93], v[94:95], 0, v[146:147]
	global_load_dword a60, v[92:93], off
	global_load_dword a44, v[92:93], off offset:128
	v_add_lshl_u32 v94, v135, v132, 12
	v_lshl_add_u64 v[92:93], v[94:95], 0, v[146:147]
	global_load_dword a61, v[92:93], off
	global_load_dword a45, v[92:93], off offset:128
	v_add_lshl_u32 v94, v135, v133, 12
	v_lshl_add_u64 v[92:93], v[94:95], 0, v[146:147]
	global_load_dword a62, v[92:93], off
; __device__ __forceinline__ u16 f2bf(float f) { return (u16)(pack2(f, f) & 0xffffu); }
; __device__ __forceinline__ float sum32(float v) { v = dpp_row_sum16(v); v += __shfl_xor(v, 16); return v; }
; __device__ __forceinline__ int rowmap(int e, int lane) { return (e & 3) + 8 * (e >> 2) + 4 * (lane >> 5); }
; __device__ __forceinline__ void phase4b(const Params& p, char* smem) {
;     ...
;     for (int i = 0; i < 2; i++)
; #pragma unroll
;       for (int e = 0; e < 16; e++) {
;         const int row = m0 + wm * 64 + i * 32 + rowmap(e, lane);
;         const float* xr = xrow(p, row);
;         float sq = 0.f;
; #pragma unroll
;         for (int j = 0; j < 2; j++) {
;           const int col = n0 + wn * 64 + j * 32 + (lane & 31);
;           float v = acc[i][j][e] + xr[col];
;           X1[(size_t)row * 1024 + col] = v;
;           ((u16*)smem)[(row - m0) * 136 + (col - n0)] = f2bf(v);
;           sq += v * v;
;         }
;         sq = sum32(sq);
;         if ((lane & 31) == 0) atomicAdd(&SSQ1[row], sq);
	global_load_dword a46, v[92:93], off offset:128
	v_add_lshl_u32 v94, v135, v134, 12
	v_lshl_add_u64 v[92:93], v[94:95], 0, v[146:147]
	global_load_dword a63, v[92:93], off
	global_load_dword a47, v[92:93], off offset:128
	v_add_lshl_u32 v94, v148, v117, 12
	v_lshl_add_u64 v[92:93], v[94:95], 0, v[146:147]
	global_load_dword a16, v[92:93], off
	global_load_dword a0, v[92:93], off offset:128
	v_add_lshl_u32 v94, v148, v120, 12
	v_lshl_add_u64 v[92:93], v[94:95], 0, v[146:147]
	global_load_dword a17, v[92:93], off
	global_load_dword a1, v[92:93], off offset:128
	v_add_lshl_u32 v94, v148, v121, 12
	v_lshl_add_u64 v[92:93], v[94:95], 0, v[146:147]
	global_load_dword a18, v[92:93], off
	global_load_dword a2, v[92:93], off offset:128
	v_add_lshl_u32 v94, v148, v122, 12
	v_lshl_add_u64 v[92:93], v[94:95], 0, v[146:147]
	global_load_dword a19, v[92:93], off
	global_load_dword a3, v[92:93], off offset:128
	v_add_lshl_u32 v94, v148, v123, 12
	v_lshl_add_u64 v[92:93], v[94:95], 0, v[146:147]
	global_load_dword a20, v[92:93], off
	global_load_dword a4, v[92:93], off offset:128
	v_add_lshl_u32 v94, v148, v124, 12
	v_lshl_add_u64 v[92:93], v[94:95], 0, v[146:147]
	global_load_dword a21, v[92:93], off
	global_load_dword a5, v[92:93], off offset:128
	v_add_lshl_u32 v94, v148, v125, 12
	v_lshl_add_u64 v[92:93], v[94:95], 0, v[146:147]
	global_load_dword a22, v[92:93], off
	global_load_dword a6, v[92:93], off offset:128
	v_add_lshl_u32 v94, v148, v126, 12
	v_lshl_add_u64 v[92:93], v[94:95], 0, v[146:147]
	global_load_dword a23, v[92:93], off
	global_load_dword a7, v[92:93], off offset:128
	v_add_lshl_u32 v94, v148, v127, 12
	v_lshl_add_u64 v[92:93], v[94:95], 0, v[146:147]
	global_load_dword a24, v[92:93], off
	global_load_dword a8, v[92:93], off offset:128
	v_add_lshl_u32 v94, v148, v128, 12
	v_lshl_add_u64 v[92:93], v[94:95], 0, v[146:147]
	global_load_dword a25, v[92:93], off
	global_load_dword a9, v[92:93], off offset:128
	v_add_lshl_u32 v94, v148, v129, 12
	v_lshl_add_u64 v[92:93], v[94:95], 0, v[146:147]
	global_load_dword a26, v[92:93], off
	global_load_dword a10, v[92:93], off offset:128
	v_add_lshl_u32 v94, v148, v130, 12
	v_lshl_add_u64 v[92:93], v[94:95], 0, v[146:147]
	global_load_dword a27, v[92:93], off
	global_load_dword a11, v[92:93], off offset:128
	v_add_lshl_u32 v94, v148, v131, 12
	v_lshl_add_u64 v[92:93], v[94:95], 0, v[146:147]
	global_load_dword a28, v[92:93], off
	global_load_dword a12, v[92:93], off offset:128
	v_add_lshl_u32 v94, v148, v132, 12
	v_lshl_add_u64 v[92:93], v[94:95], 0, v[146:147]
	global_load_dword a29, v[92:93], off
	global_load_dword a13, v[92:93], off offset:128
	v_add_lshl_u32 v94, v148, v133, 12
	v_lshl_add_u64 v[92:93], v[94:95], 0, v[146:147]
	global_load_dword a30, v[92:93], off
	global_load_dword a14, v[92:93], off offset:128
	v_add_lshl_u32 v94, v148, v134, 12
	v_lshl_add_u64 v[92:93], v[94:95], 0, v[146:147]
	global_load_dword a31, v[92:93], off
	global_load_dword a15, v[92:93], off offset:128
	s_waitcnt vmcnt(0)
	v_add_u32_e32 v135, s6, v105
	v_or_b32_e32 v94, v135, v117
	v_add_u32_e32 v64, 0xffffc000, v94
	v_cmp_gt_i32_e32 vcc, s14, v94
	v_ashrrev_i32_e32 v95, 31, v94
	v_mov_b32_e32 v137, s41
	v_cndmask_b32_e32 v92, v64, v94, vcc
	v_mov_b32_e32 v64, s43
	v_cndmask_b32_e32 v93, 0, v95, vcc
	v_cndmask_b32_e32 v147, v64, v137, vcc
	v_mov_b32_e32 v64, s42
	v_mov_b32_e32 v137, s40
	v_cndmask_b32_e32 v146, v64, v137, vcc
	v_lshlrev_b64 v[92:93], 12, v[92:93]
	v_or_b32_e32 v64, s45, v107
	v_lshl_add_u64 v[146:147], v[146:147], 0, v[92:93]
	v_lshlrev_b32_e32 v64, 2, v64
	v_lshl_add_u64 v[92:93], v[146:147], 0, v[64:65]
	v_accvgpr_read_b32 v137, a48
	v_lshlrev_b64 v[148:149], 12, v[94:95]
	v_add_u32_e32 v92, s45, v107
	v_lshl_add_u64 v[148:149], s[78:79], 0, v[148:149]
	v_mov_b32_e32 v93, v65
	v_lshlrev_b32_e32 v92, 2, v92
	v_lshl_add_u64 v[150:151], v[148:149], 0, v[64:65]
	v_lshl_add_u64 v[146:147], v[146:147], 0, v[92:93]
	v_lshl_add_u64 v[148:149], v[148:149], 0, v[92:93]
	v_add_f32_e32 v48, v48, v137
	global_store_dword v[150:151], v48, off
	v_accvgpr_read_b32 v137, a32
	v_cvt_pk_bf16_f32 v150, v48, s0
	v_subrev_u32_e32 v146, s6, v94
	v_mad_u64_u32 v[146:147], s[8:9], v146, s15, v[68:69]
	ds_write_b16 v146, v150
	v_add_f32_e32 v137, v32, v137
	v_mul_f32_e32 v32, v137, v137
	v_fmac_f32_e32 v32, v48, v48
	global_store_dword v[148:149], v137, off offset:128
	v_cvt_pk_bf16_f32 v137, v137, s0
	v_add_f32_dpp v32, v32, v32 quad_perm:[1,0,3,2] row_mask:0xf bank_mask:0xf bound_ctrl:1
	ds_write_b16 v146, v137 offset:64
	s_nop 0
	v_add_f32_dpp v32, v32, v32 quad_perm:[2,3,0,1] row_mask:0xf bank_mask:0xf bound_ctrl:1
	s_nop 1
	v_add_f32_dpp v32, v32, v32 row_half_mirror row_mask:0xf bank_mask:0xf bound_ctrl:1
	s_nop 1
	v_add_f32_dpp v32, v32, v32 row_mirror row_mask:0xf bank_mask:0xf bound_ctrl:1
	v_mov_b32_e32 v48, v32
	s_nop 1
	v_permlane16_swap_b32_e32 v48, v48
	s_and_saveexec_b64 s[8:9], s[4:5]
	s_cbranch_execz .LBB0_1299
	v_add_f32_e32 v32, v32, v48
	v_lshl_add_u64 v[94:95], v[94:95], 2, s[94:95]
	global_atomic_add_f32 v[94:95], v32, off
